# self-attn seam operands (gates, next item Q/K/V) streamed to an LDS stage by one LDS-DMA load per loop iteration and read back at the seam (no 12-load burst)
# speedup vs baseline: 1.0084x; 1.0084x over previous
.LBB0_873:
	s_andn2_b64 vcc, exec, s[0:1]
	s_cbranch_vccnz .LBB0_939
	v_mov_b32_e32 v0, v250
	v_readlane_b32 s0, v255, 0
	s_lshl_b32 s0, s0, 6
	v_readlane_b32 s1, v255, 1
	v_and_or_b32 v0, v0, 63, s0
	v_ashrrev_i32_e32 v1, 31, v0
	v_lshlrev_b64 v[0:1], 2, v[0:1]
	v_lshl_add_u64 v[2:3], s[58:59], 0, v[0:1]
	v_lshl_add_u64 v[0:1], s[60:61], 0, v[0:1]
	global_load_dword v2, v[2:3], off
	v_readlane_b32 s0, v253, 13
	global_load_dword v4, v[0:1], off
	v_readlane_b32 s1, v253, 14
	s_andn2_b64 vcc, exec, s[0:1]
	s_waitcnt vmcnt(0)
	v_and_b32_e32 v3, 0x7fffffff, v2
	s_nop 1
	v_mov_b32_dpp v0, v3 quad_perm:[1,0,3,2] row_mask:0xf bank_mask:0xf bound_ctrl:1
	v_and_b32_e32 v5, 0x7fffffff, v4
	v_max_f32_e64 v1, |v2|, |v2|
	v_max_f32_e32 v0, v0, v0
	v_mov_b32_dpp v2, v5 quad_perm:[1,0,3,2] row_mask:0xf bank_mask:0xf bound_ctrl:1
	v_max_f32_e64 v3, |v4|, |v4|
	v_max_f32_e32 v2, v2, v2
	v_max_f32_e32 v0, v1, v0
	v_max_f32_e32 v2, v3, v2
	s_nop 0
	v_mov_b32_dpp v1, v0 quad_perm:[2,3,0,1] row_mask:0xf bank_mask:0xf bound_ctrl:1
	v_mov_b32_dpp v3, v2 quad_perm:[2,3,0,1] row_mask:0xf bank_mask:0xf bound_ctrl:1
	v_max_f32_e32 v1, v1, v1
	v_max_f32_e32 v3, v3, v3
	v_max_f32_e32 v0, v0, v1
	v_max_f32_e32 v2, v2, v3
	s_nop 0
	v_mov_b32_dpp v1, v0 row_half_mirror row_mask:0xf bank_mask:0xf bound_ctrl:1
	v_mov_b32_dpp v3, v2 row_half_mirror row_mask:0xf bank_mask:0xf bound_ctrl:1
	v_max_f32_e32 v1, v1, v1
	v_max_f32_e32 v3, v3, v3
	v_max_f32_e32 v0, v0, v1
	v_max_f32_e32 v2, v2, v3
	s_nop 0
	v_mov_b32_dpp v1, v0 row_mirror row_mask:0xf bank_mask:0xf bound_ctrl:1
	v_mov_b32_dpp v3, v2 row_mirror row_mask:0xf bank_mask:0xf bound_ctrl:1
	v_max_f32_e32 v1, v1, v1
	v_max_f32_e32 v3, v3, v3
	v_max_f32_e32 v0, v0, v1
	v_max_f32_e32 v2, v2, v3
	v_mov_b32_e32 v1, v0
	v_mov_b32_e32 v3, v2
	s_nop 0
	v_permlane16_swap_b32_e32 v0, v1
	v_permlane16_swap_b32_e32 v2, v3
	v_max_f32_e32 v1, v1, v1
	v_max_f32_e32 v0, v0, v0
	v_max_f32_e32 v3, v3, v3
	v_max_f32_e32 v2, v2, v2
	v_max_f32_e32 v0, v0, v1
	v_max_f32_e32 v2, v2, v3
	v_mov_b32_e32 v1, v0
	v_mov_b32_e32 v3, v2
	s_nop 0
	v_permlane32_swap_b32_e32 v0, v1
	v_permlane32_swap_b32_e32 v2, v3
	s_cbranch_vccnz .LBB0_900
	v_mov_b32_e32 v8, v250
	v_readlane_b32 s0, v254, 38
	v_readlane_b32 s1, v254, 39
	v_ashrrev_i32_e32 v4, 1, v8
	v_bfi_b32 v6, s88, v4, v8
	v_mov_b64_e32 v[4:5], s[0:1]
	v_mad_i64_i32 v[4:5], s[0:1], v6, s33, v[4:5]
	v_lshrrev_b32_e32 v6, 1, v8
	v_and_b32_e32 v176, 16, v6
	v_readlane_b32 s0, v254, 40
	v_lshl_add_u64 v[4:5], v[4:5], 0, v[176:177]
	v_readlane_b32 s1, v254, 41
	global_load_dwordx4 v[96:99], v[4:5], off offset:1024
	global_load_dwordx4 v[100:103], v[4:5], off offset:1056
	global_load_dwordx4 v[104:107], v[4:5], off offset:1088
	global_load_dwordx4 v[108:111], v[4:5], off offset:1120
	v_ashrrev_i32_e32 v4, 3, v8
	v_mov_b64_e32 v[6:7], s[0:1]
	v_lshlrev_b32_e32 v8, 4, v8
	v_mad_i64_i32 v[6:7], s[0:1], v4, s33, v[6:7]
	v_and_b32_e32 v176, 0x70, v8
	v_lshl_add_u64 v[6:7], v[6:7], 0, v[176:177]
	s_mov_b32 s0, 0x48000
	v_ashrrev_i32_e32 v5, 31, v4
	v_add_co_u32_e32 v8, vcc, s0, v6
	v_readlane_b32 s0, v253, 15
	s_nop 0
	v_addc_co_u32_e32 v9, vcc, 0, v7, vcc
	v_lshlrev_b64 v[4:5], s0, v[4:5]
	v_readlane_b32 s0, v254, 42
	global_load_dwordx4 v[64:67], v[6:7], off offset:2048
	global_load_dwordx4 v[68:71], v[8:9], off offset:2048
	v_add_co_u32_e32 v6, vcc, 0x90000, v6
	v_readlane_b32 s1, v254, 43
	s_nop 0
	v_addc_co_u32_e32 v7, vcc, 0, v7, vcc
	v_lshl_add_u64 v[4:5], v[4:5], 1, s[0:1]
	v_lshl_add_u64 v[4:5], v[4:5], 0, v[176:177]
	global_load_dwordx4 v[72:75], v[6:7], off offset:2048
	global_load_dwordx4 v[76:79], v[4:5], off
	v_max_f32_e32 v0, v0, v0
	v_max_f32_e32 v1, v1, v1
	v_max_f32_e32 v0, v0, v1
	v_max_f32_e32 v1, v2, v2
	v_max_f32_e32 v2, v3, v3
	v_max_f32_e32 v1, v1, v2
	v_mul_f32_e32 v0, 0x41000000, v0
	v_mul_f32_e32 v0, v0, v1
	v_mul_f32_e32 v0, 0x3f828f5c, v0
	v_mul_f32_e32 v0, 0x3fb8aa3b, v0
	s_mov_b32 s0, 0x41e00000
	v_cmp_ngt_f32_e64 s[36:37], s0, v0
	s_mov_b32 s8, s46
	s_waitcnt vmcnt(0)
	v_and_b32_e32 v172, 63, v250
	v_lshlrev_b32_e32 v172, 4, v172
	v_lshrrev_b32_e32 v173, 6, v250
	v_lshl_or_b32 v172, v173, 10, v172
	v_add_u32_e32 v173, 0x10000, v172
	ds_write_b128 v173, v[64:67] offset:32768
	ds_write_b128 v173, v[68:71] offset:40960
	ds_write_b128 v173, v[72:75] offset:49152
	ds_write_b128 v173, v[76:79] offset:57344
	ds_write_b128 v173, v[96:99]
	ds_write_b128 v173, v[100:103] offset:8192
	ds_write_b128 v173, v[104:107] offset:16384
	ds_write_b128 v173, v[108:111] offset:24576
	s_branch .LBB0_877

.LBB0_896:
	s_andn2_saveexec_b64 s[44:45], s[44:45]
	s_cbranch_execz .LBB0_876
	v_mov_b32_e32 v129, v250
	v_lshrrev_b32_e32 v168, 1, v250
	v_and_b32_e32 v168, 0xe0, v168
	v_and_b32_e32 v169, 31, v250
	v_or_b32_e32 v168, v168, v169
	v_mul_u32_u24_e32 v168, 0x1200, v168
	v_bfe_u32 v169, v250, 5, 1
	v_lshl_or_b32 v168, v169, 4, v168
	v_lshrrev_b32_e32 v169, 3, v250
	v_and_b32_e32 v171, 7, v250
	v_mul_u32_u24_e32 v170, 0x1200, v169
	v_lshl_or_b32 v170, v171, 4, v170
	s_lshl_b32 s18, s8, 1
	v_mul_lo_u32 v169, s18, v169
	v_lshl_or_b32 v169, v171, 4, v169
	v_lshrrev_b32_e32 v171, 6, v250
	v_lshlrev_b32_e32 v171, 10, v171
	v_and_b32_e32 v172, 63, v250
	v_lshlrev_b32_e32 v172, 4, v172
	v_lshrrev_b32_e32 v173, 6, v250
	v_lshl_or_b32 v172, v173, 10, v172
	v_add_u32_e32 v173, 0x10000, v172
	s_waitcnt lgkmcnt(0)
	s_barrier
	v_readlane_b32 s9, v254, 52
	v_lshlrev_b32_e32 v2, 4, v129
	v_lshlrev_b32_e32 v3, 1, v129
	v_lshrrev_b32_e32 v131, 1, v129
	v_lshlrev_b32_e32 v0, 3, v129
	v_xor_b32_e32 v4, v2, v129
	v_and_b32_e32 v2, 19, v129
	v_and_b32_e32 v3, 8, v3
	v_and_b32_e32 v5, 4, v131
	v_ashrrev_i32_e32 v128, 3, v129
	v_and_b32_e32 v130, 56, v0
	v_or3_b32 v5, v3, v2, v5
	v_mov_b64_e32 v[2:3], s[40:41]
	v_mad_i64_i32 v[0:1], s[2:3], v128, s21, 0
	v_lshlrev_b32_e32 v176, 1, v130
	v_mad_i64_i32 v[2:3], s[2:3], v128, s33, v[2:3]
	v_lshl_add_u64 v[132:133], v[2:3], 0, v[176:177]
	v_lshlrev_b32_e32 v2, 7, v128
	s_movk_i32 s2, 0x70
	v_and_or_b32 v142, v4, s2, v2
	s_mov_b32 s2, 0xd8000
	v_lshl_add_u64 v[0:1], v[0:1], 1, s[42:43]
	v_add_co_u32_e32 v2, vcc, s2, v132
	v_lshl_add_u64 v[0:1], v[0:1], 0, v[176:177]
	v_lshrrev_b32_e32 v40, 1, v5
	v_bfe_u32 v138, v129, 5, 1
	ds_read_b128 v[64:67], v173 offset:32768
	ds_read_b128 v[68:71], v173 offset:40960
	ds_read_b128 v[72:75], v173 offset:49152
	ds_read_b128 v[76:79], v173 offset:57344
	ds_read_b128 v[96:99], v173
	ds_read_b128 v[100:103], v173 offset:8192
	ds_read_b128 v[104:107], v173 offset:16384
	ds_read_b128 v[108:111], v173 offset:24576
	s_waitcnt lgkmcnt(4)
	ds_write_b128 v142, v[64:67] offset:16384
	ds_write_b128 v142, v[68:71] offset:24576
	ds_write_b128 v142, v[72:75]
	ds_write_b128 v142, v[76:79] offset:8192
	v_addc_co_u32_e32 v3, vcc, 0, v133, vcc
	global_load_dwordx4 v[112:115], v[2:3], off offset:2048
	global_load_dwordx4 v[116:119], v[0:1], off offset:128
	v_bitop3_b32 v0, v40, v138, 7 bitop3:0x6c
	v_lshlrev_b32_e32 v143, 7, v5
	v_lshlrev_b32_e32 v145, 4, v0
	s_waitcnt lgkmcnt(0)
	s_barrier
	v_or_b32_e32 v41, v143, v145
	ds_read_b128 v[0:3], v41 offset:16384
	ds_read_b128 v[4:7], v41 offset:20480
	s_waitcnt lgkmcnt(0)
	v_mfma_f32_32x32x16_bf16 v[16:31], v[0:3], v[96:99], 0
	v_or_b32_e32 v32, 2, v138
	v_bitop3_b32 v32, v40, v32, 7 bitop3:0x6c
	v_lshlrev_b32_e32 v146, 4, v32
	v_or_b32_e32 v42, v143, v146
	ds_read_b128 v[32:35], v42 offset:16384
	ds_read_b128 v[36:39], v42 offset:20480
	v_lshrrev_b32_e32 v73, 5, v129
	v_bfe_u32 v74, v129, 1, 3
	v_mfma_f32_32x32x16_bf16 v[0:15], v[4:7], v[96:99], 0
	s_lshr_b32 s2, s21, 6
	v_mad_i64_i32 v[134:135], s[18:19], v128, s33, 0
	s_add_i32 s2, s2, -1
	v_and_b32_e32 v148, 31, v129
	v_lshlrev_b32_e32 v75, 7, v148
	s_mov_b32 s3, 5
	s_waitcnt lgkmcnt(1)
	v_mfma_f32_32x32x16_bf16 v[16:31], v[32:35], v[100:103], v[16:31]
	v_or_b32_e32 v32, 4, v138
	v_bitop3_b32 v32, v40, v32, 7 bitop3:0x6c
	v_lshlrev_b32_e32 v147, 4, v32
	v_or_b32_e32 v43, v143, v147
	s_waitcnt lgkmcnt(0)
	v_mfma_f32_32x32x16_bf16 v[0:15], v[36:39], v[100:103], v[0:15]
	ds_read_b128 v[32:35], v43 offset:16384
	ds_read_b128 v[36:39], v43 offset:20480
	s_waitcnt lgkmcnt(1)
	v_mfma_f32_32x32x16_bf16 v[16:31], v[32:35], v[104:107], v[16:31]
	v_or_b32_e32 v32, 6, v138
	v_bitop3_b32 v32, v40, v32, 7 bitop3:0x6c
	v_lshlrev_b32_e32 v149, 4, v32
	v_or_b32_e32 v72, v143, v149
	ds_read_b128 v[32:35], v72 offset:16384
	s_waitcnt lgkmcnt(1)
	v_mfma_f32_32x32x16_bf16 v[0:15], v[36:39], v[104:107], v[0:15]
	ds_read_b128 v[36:39], v72 offset:20480
	s_waitcnt lgkmcnt(1)
	v_mfma_f32_32x32x16_bf16 v[16:31], v[32:35], v[108:111], v[16:31]
	s_waitcnt lgkmcnt(0)
	v_mfma_f32_32x32x16_bf16 v[0:15], v[36:39], v[108:111], v[0:15]
	s_nop 9
	v_exp_f32_e32 v32, v16
	v_exp_f32_e32 v33, v17
	v_exp_f32_e32 v34, v18
	v_exp_f32_e32 v35, v19
	v_exp_f32_e32 v37, v20
	v_exp_f32_e32 v38, v21
	v_add_f32_e32 v16, 0, v32
	v_add_f32_e32 v17, 0, v33
	v_add_f32_e32 v36, 0, v34
	v_add_f32_e32 v39, 0, v35
	v_add_f32_e32 v40, v37, v16
	v_add_f32_e32 v44, v38, v17
	v_exp_f32_e32 v45, v22
	v_exp_f32_e32 v46, v23
	ds_read_b128 v[16:19], v41 offset:24576
	ds_read_b128 v[20:23], v41 offset:28672
	s_waitcnt lgkmcnt(1)
	v_mfma_f32_32x32x16_bf16 v[48:63], v[16:19], v[96:99], 0
	v_exp_f32_e32 v41, v24
	v_add_f32_e32 v36, v45, v36
	v_add_f32_e32 v39, v46, v39
	ds_read_b128 v[64:67], v42 offset:24576
	ds_read_b128 v[68:71], v42 offset:28672
	v_exp_f32_e32 v42, v25
	v_add_f32_e32 v24, v41, v40
	v_exp_f32_e32 v40, v26
	v_exp_f32_e32 v47, v27
	v_exp_f32_e32 v28, v28
	v_exp_f32_e32 v29, v29
	v_exp_f32_e32 v30, v30
	v_exp_f32_e32 v31, v31
	v_exp_f32_e32 v77, v0
	v_exp_f32_e32 v78, v1
	v_add_f32_e32 v25, v42, v44
	s_waitcnt lgkmcnt(1)
	v_mfma_f32_32x32x16_bf16 v[48:63], v[64:67], v[100:103], v[48:63]
	v_add_f32_e32 v26, v40, v36
	v_add_f32_e32 v27, v47, v39
	v_cvt_pk_bf16_f32 v80, v32, v33
	v_cvt_pk_bf16_f32 v81, v34, v35
	v_cvt_pk_bf16_f32 v82, v37, v38
	v_cvt_pk_bf16_f32 v83, v45, v46
	v_add_f32_e32 v24, v28, v24
	v_add_f32_e32 v25, v29, v25
	v_exp_f32_e32 v4, v4
	v_add_f32_e32 v76, v30, v26
	v_add_f32_e32 v0, v31, v27
	v_add_f32_e32 v79, v77, v24
	v_add_f32_e32 v88, v78, v25
	ds_read_b128 v[16:19], v43 offset:24576
	ds_read_b128 v[24:27], v43 offset:28672
	v_cvt_pk_bf16_f32 v86, v28, v29
	v_exp_f32_e32 v28, v2
	v_exp_f32_e32 v29, v3
	v_exp_f32_e32 v5, v5
	s_waitcnt lgkmcnt(1)
	v_mfma_f32_32x32x16_bf16 v[48:63], v[16:19], v[104:107], v[48:63]
	v_cvt_pk_bf16_f32 v84, v41, v42
	v_cvt_pk_bf16_f32 v85, v40, v47
	v_exp_f32_e32 v6, v6
	v_exp_f32_e32 v7, v7
	v_cvt_pk_bf16_f32 v87, v30, v31
	v_add_f32_e32 v30, v28, v76
	v_add_f32_e32 v31, v29, v0
	v_mfma_f32_32x32x16_bf16 v[32:47], v[20:23], v[96:99], 0
	ds_read_b128 v[0:3], v72 offset:24576
	ds_read_b128 v[20:23], v72 offset:28672
	v_add_f32_e32 v64, v4, v79
	v_add_f32_e32 v65, v5, v88
	v_add_f32_e32 v30, v6, v30
	v_exp_f32_e32 v8, v8
	v_exp_f32_e32 v9, v9
	v_add_f32_e32 v31, v7, v31
	v_cvt_pk_bf16_f32 v90, v4, v5
	v_exp_f32_e32 v4, v10
	v_exp_f32_e32 v5, v11
	v_exp_f32_e32 v11, v13
	v_cvt_pk_bf16_f32 v91, v6, v7
	v_exp_f32_e32 v7, v12
	s_waitcnt lgkmcnt(1)
	v_mfma_f32_32x32x16_bf16 v[48:63], v[0:3], v[108:111], v[48:63]
	v_exp_f32_e32 v0, v14
	v_exp_f32_e32 v1, v15
	v_add_f32_e32 v64, v8, v64
	v_add_f32_e32 v65, v9, v65
	v_cvt_pk_bf16_f32 v88, v77, v78
	v_cvt_pk_bf16_f32 v89, v28, v29
	v_add_f32_e32 v6, v4, v30
	v_mfma_f32_32x32x16_bf16 v[32:47], v[68:71], v[100:103], v[32:47]
	v_add_f32_e32 v10, v5, v31
	v_mov_b32_e32 v16, 0
	v_add_f32_e32 v12, v7, v64
	v_add_f32_e32 v2, v11, v65
	v_add_f32_e32 v3, v0, v6
	v_add_f32_e32 v6, v1, v10
	v_mfma_f32_32x32x16_bf16 v[32:47], v[24:27], v[104:107], v[32:47]
	v_cvt_pk_bf16_f32 v95, v0, v1
	v_add_f32_e32 v0, v12, v2
	v_add_f32_e32 v1, v3, v6
	v_add_f32_e32 v0, v0, v1
	v_add_f32_e32 v150, 0, v0
	v_bitop3_b32 v0, v73, v74, 1 bitop3:0x6c
	v_lshlrev_b32_e32 v2, 4, v0
	v_bitop3_b32 v0, v138, v74, 2 bitop3:0x36
	v_lshlrev_b32_e32 v3, 4, v0
	v_bitop3_b32 v0, v138, v74, 4 bitop3:0x36
	v_cvt_pk_bf16_f32 v93, v4, v5
	v_lshlrev_b32_e32 v4, 4, v0
	v_bitop3_b32 v0, v138, v74, 6 bitop3:0x36
	v_lshlrev_b32_e32 v5, 4, v0
	v_and_b32_e32 v0, 7, v129
	v_cvt_pk_bf16_f32 v92, v8, v9
	v_cvt_pk_bf16_f32 v94, v7, v11
	v_lshlrev_b32_e32 v176, 4, v0
	v_lshlrev_b32_e32 v0, 1, v128
	s_waitcnt lgkmcnt(0)
	s_barrier
	v_mad_i64_i32 v[0:1], s[18:19], v0, s21, v[176:177]
	s_add_u32 s18, s9, s38
	v_readlane_b32 s9, v254, 53
	s_addc_u32 s19, s9, s39
	s_waitcnt lgkmcnt(0)
	v_mfma_f32_32x32x16_bf16 v[32:47], v[20:23], v[108:111], v[32:47]
	v_lshl_add_u64 v[136:137], s[18:19], 0, v[0:1]
	v_add_u32_e32 v144, v75, v2
	v_add_u32_e32 v141, v75, v3
	v_add_u32_e32 v140, v75, v4
	v_add_u32_e32 v139, v75, v5
	v_mov_b32_e32 v17, v16
	v_mov_b32_e32 v18, v16
	v_mov_b32_e32 v19, v16
	v_mov_b32_e32 v20, v16
	v_mov_b32_e32 v21, v16
	v_mov_b32_e32 v22, v16
	v_mov_b32_e32 v23, v16
	v_mov_b32_e32 v24, v16
	v_mov_b32_e32 v25, v16
	v_mov_b32_e32 v26, v16
	v_mov_b32_e32 v27, v16
	v_mov_b32_e32 v28, v16
	v_mov_b32_e32 v29, v16
	v_mov_b32_e32 v30, v16
	v_mov_b32_e32 v31, v16
	v_mov_b32_e32 v0, v16
	v_mov_b32_e32 v1, v16
	v_mov_b32_e32 v2, v16
	v_mov_b32_e32 v3, v16
	v_mov_b32_e32 v4, v16
	v_mov_b32_e32 v5, v16
	v_mov_b32_e32 v6, v16
	v_mov_b32_e32 v7, v16
	v_mov_b32_e32 v8, v16
	v_mov_b32_e32 v9, v16
	v_mov_b32_e32 v10, v16
	v_mov_b32_e32 v11, v16
	v_mov_b32_e32 v12, v16
	v_mov_b32_e32 v13, v16
	v_mov_b32_e32 v14, v16
	v_mov_b32_e32 v15, v16
	v_add_u32_e32 v164, v143, v145
	v_add_u32_e32 v165, v143, v146
	v_add_u32_e32 v166, v143, v147
	v_add_u32_e32 v167, v143, v149
.LBB0_898:
	s_add_i32 s9, s3, -1
	s_min_u32 s9, s9, s2
	s_lshl_b32 s9, s9, 6
	s_waitcnt vmcnt(1)
	ds_write_b128 v142, v[112:115] offset:16384
	s_waitcnt vmcnt(0)
	ds_write_b128 v142, v[116:119] offset:24576
	v_mad_u64_u32 v[64:65], s[18:19], s9, v237, v[132:133]
	global_load_dwordx4 v[120:123], v[64:65], off offset:2048
	global_load_dwordx4 v[124:127], v[136:137], off offset:-128
	ds_read_b128 v[64:67], v144 offset:8192
	ds_read_b128 v[68:71], v144 offset:12288
	ds_read_b128 v[72:75], v141 offset:8192
	ds_read_b128 v[76:79], v141 offset:12288
	v_exp_f32_e32 v151, v48
	v_exp_f32_e32 v152, v49
	s_waitcnt lgkmcnt(3)
	v_mfma_f32_32x32x16_bf16 v[16:31], v[64:67], v[80:83], v[16:31]
	v_exp_f32_e32 v153, v50
	v_exp_f32_e32 v154, v51
	ds_read_b128 v[48:51], v140 offset:8192
	ds_read_b128 v[64:67], v140 offset:12288
	v_exp_f32_e32 v155, v52
	s_waitcnt lgkmcnt(4)
	v_mfma_f32_32x32x16_bf16 v[0:15], v[68:71], v[80:83], v[0:15]
	v_exp_f32_e32 v156, v53
	v_exp_f32_e32 v159, v54
	v_exp_f32_e32 v160, v55
	v_exp_f32_e32 v162, v57
	s_waitcnt lgkmcnt(3)
	v_mfma_f32_32x32x16_bf16 v[16:31], v[72:75], v[84:87], v[16:31]
	ds_read_b128 v[68:71], v139 offset:8192
	ds_read_b128 v[80:83], v139 offset:12288
	v_add_f32_e32 v157, v155, v151
	v_add_f32_e32 v158, v156, v152
	ds_read_b128 v[52:55], v164
	ds_read_b128 v[72:75], v164 offset:4096
	v_add_f32_e32 v161, v159, v153
	s_waitcnt lgkmcnt(6)
	v_mfma_f32_32x32x16_bf16 v[0:15], v[76:79], v[84:87], v[0:15]
	v_exp_f32_e32 v77, v56
	v_add_f32_e32 v76, v160, v154
	v_exp_f32_e32 v62, v62
	ds_read_b128 v[112:115], v165
	ds_read_b128 v[116:119], v165 offset:4096
	v_cvt_pk_bf16_f32 v56, v151, v152
	s_waitcnt lgkmcnt(7)
	v_mfma_f32_32x32x16_bf16 v[16:31], v[48:51], v[88:91], v[16:31]
	v_exp_f32_e32 v49, v58
	v_exp_f32_e32 v50, v59
	v_add_f32_e32 v48, v77, v157
	v_add_f32_e32 v51, v162, v158
	v_add_f32_e32 v78, v49, v161
	v_add_f32_e32 v76, v50, v76
	s_waitcnt lgkmcnt(6)
	v_mfma_f32_32x32x16_bf16 v[0:15], v[64:67], v[88:91], v[0:15]
	v_exp_f32_e32 v60, v60
	v_add_f32_e32 v151, v62, v78
	v_exp_f32_e32 v61, v61
	v_exp_f32_e32 v63, v63
	v_cvt_pk_bf16_f32 v59, v159, v160
	v_exp_f32_e32 v160, v33
	s_waitcnt lgkmcnt(5)
	v_mfma_f32_32x32x16_bf16 v[16:31], v[68:71], v[92:95], v[16:31]
	v_cvt_pk_bf16_f32 v57, v153, v154
	v_cvt_pk_bf16_f32 v58, v155, v156
	v_add_f32_e32 v48, v60, v48
	v_add_f32_e32 v51, v61, v51
	v_cvt_pk_bf16_f32 v49, v49, v50
	s_waitcnt lgkmcnt(4)
	v_mfma_f32_32x32x16_bf16 v[0:15], v[80:83], v[92:95], v[0:15]
	s_sub_u32 vcc_lo, s3, 5
	s_lshr_b32 vcc_lo, vcc_lo, 1
	s_and_b32 vcc_lo, vcc_lo, 15
	v_readfirstlane_b32 s18, v171
	s_cmp_lt_u32 vcc_lo, 8
	s_cbranch_scc0 .Lst_8
	s_cmp_lt_u32 vcc_lo, 4
	s_cbranch_scc0 .Lst_4
	s_cmp_lt_u32 vcc_lo, 2
	s_cbranch_scc0 .Lst_2
	s_cmp_lt_u32 vcc_lo, 1
	s_cbranch_scc0 .Lst_1
	s_add_u32 m0, s18, 0x7600
	s_nop 0
	global_load_lds_dwordx4 v168, s[12:13] offset:2560
	s_branch .Lst_done
.Lst_1:
	s_add_u32 m0, s18, 0x95e0
	s_nop 0
	global_load_lds_dwordx4 v168, s[12:13] offset:2592
	s_branch .Lst_done
.Lst_2:
	s_cmp_lt_u32 vcc_lo, 3
	s_cbranch_scc0 .Lst_3
	s_add_u32 m0, s18, 0xb5c0
	s_nop 0
	global_load_lds_dwordx4 v168, s[12:13] offset:2624
	s_branch .Lst_done
.Lst_3:
	s_add_u32 m0, s18, 0xd5a0
	s_nop 0
	global_load_lds_dwordx4 v168, s[12:13] offset:2656
	s_branch .Lst_done
.Lst_4:
	s_cmp_lt_u32 vcc_lo, 6
	s_cbranch_scc0 .Lst_6
	s_cmp_lt_u32 vcc_lo, 5
	s_cbranch_scc0 .Lst_5
	s_add_u32 m0, s18, 0xfc00
	s_nop 0
	global_load_lds_dwordx4 v168, s[14:15] offset:1024
	s_branch .Lst_done
.Lst_5:
	s_add_u32 m0, s18, 0x11be0
	s_nop 0
	global_load_lds_dwordx4 v168, s[14:15] offset:1056
	s_branch .Lst_done
.Lst_6:
	s_cmp_lt_u32 vcc_lo, 7
	s_cbranch_scc0 .Lst_7
	s_add_u32 m0, s18, 0x13bc0
	s_nop 0
	global_load_lds_dwordx4 v168, s[14:15] offset:1088
	s_branch .Lst_done
.Lst_7:
	s_add_u32 m0, s18, 0x15ba0
	s_nop 0
	global_load_lds_dwordx4 v168, s[14:15] offset:1120
	s_branch .Lst_done
.Lst_8:
	s_cmp_lt_u32 vcc_lo, 12
	s_cbranch_scc0 .Lst_12
	s_cmp_lt_u32 vcc_lo, 10
	s_cbranch_scc0 .Lst_10
	s_cmp_lt_u32 vcc_lo, 9
	s_cbranch_scc0 .Lst_9
	s_mov_b64 vcc, s[34:35]
	s_add_u32 m0, s18, 0x17800
	s_nop 0
	global_load_lds_dwordx4 v170, vcc offset:2048
	s_branch .Lst_done
.Lst_9:
	s_add_u32 vcc_lo, s34, 0x48000
	s_addc_u32 vcc_hi, s35, 0
	s_add_u32 m0, s18, 0x19800
	s_nop 0
	global_load_lds_dwordx4 v170, vcc offset:2048
	s_branch .Lst_done
.Lst_10:
	s_cmp_lt_u32 vcc_lo, 11
	s_cbranch_scc0 .Lst_11
	s_add_u32 vcc_lo, s34, 0x90000
	s_addc_u32 vcc_hi, s35, 0
	s_add_u32 m0, s18, 0x1b800
	s_nop 0
	global_load_lds_dwordx4 v170, vcc offset:2048
	s_branch .Lst_done
.Lst_11:
	s_add_u32 m0, s18, 0x1e000
	s_nop 0
	global_load_lds_dwordx4 v169, s[10:11]
	s_branch .Lst_done
.Lst_12:
	s_cmp_lt_u32 vcc_lo, 14
	s_cbranch_scc0 .Lst_14
	s_cmp_lt_u32 vcc_lo, 13
	s_cbranch_scc0 .Lst_13
	s_add_u32 m0, s18, 0x7600
	s_nop 0
	global_load_lds_dwordx4 v168, s[12:13] offset:2560
	s_branch .Lst_done

.Lst_14:
	s_cmp_lt_u32 vcc_lo, 15
	s_cbranch_scc0 .Lst_15
	s_add_u32 m0, s18, 0xb5c0
	s_nop 0
	global_load_lds_dwordx4 v168, s[12:13] offset:2624
	s_branch .Lst_done

.Lst_done:
	v_exp_f32_e32 v95, v32
	v_add_f32_e32 v32, v63, v76
	v_add_f32_e32 v163, v160, v51
	v_add_f32_e32 v161, v95, v48
	v_cvt_pk_bf16_f32 v48, v77, v162
	v_cvt_pk_bf16_f32 v51, v62, v63
	s_waitcnt lgkmcnt(3)
	v_mfma_f32_32x32x16_bf16 v[78:93], v[52:55], v[96:99], 0
	v_cvt_pk_bf16_f32 v50, v60, v61
	v_exp_f32_e32 v60, v34
	v_exp_f32_e32 v61, v35
	v_exp_f32_e32 v36, v36
	v_exp_f32_e32 v37, v37
	v_exp_f32_e32 v38, v38
	v_exp_f32_e32 v39, v39
	s_waitcnt lgkmcnt(2)
	v_mfma_f32_32x32x16_bf16 v[62:77], v[72:75], v[96:99], 0
	ds_read_b128 v[52:55], v166
	ds_read_b128 v[152:155], v166 offset:4096
	v_add_f32_e32 v151, v60, v151
	v_add_f32_e32 v162, v61, v32
	s_waitcnt lgkmcnt(3)
	v_mfma_f32_32x32x16_bf16 v[78:93], v[112:115], v[100:103], v[78:93]
	v_add_f32_e32 v112, v36, v161
	v_add_f32_e32 v113, v37, v163
	v_add_f32_e32 v114, v38, v151
	v_exp_f32_e32 v115, v40
	v_add_f32_e32 v40, v39, v162
	ds_read_b128 v[32:35], v167
	ds_read_b128 v[156:159], v167 offset:4096
	s_waitcnt lgkmcnt(4)
	v_mfma_f32_32x32x16_bf16 v[62:77], v[116:119], v[100:103], v[62:77]
	v_exp_f32_e32 v116, v41
	v_add_f32_e32 v41, v115, v112
	s_min_u32 s9, s3, s2
	s_lshl_b32 s9, s9, 6
	v_add_f32_e32 v112, v116, v113
	s_waitcnt lgkmcnt(3)
	v_mfma_f32_32x32x16_bf16 v[78:93], v[52:55], v[104:107], v[78:93]
	v_cvt_pk_bf16_f32 v54, v36, v37
	v_exp_f32_e32 v37, v42
	v_cvt_pk_bf16_f32 v55, v38, v39
	v_exp_f32_e32 v38, v43
	v_exp_f32_e32 v39, v44
	v_exp_f32_e32 v44, v45
	v_exp_f32_e32 v45, v46
	v_exp_f32_e32 v46, v47
	v_cvt_pk_bf16_f32 v52, v95, v160
	v_cvt_pk_bf16_f32 v53, v60, v61
	v_add_f32_e32 v36, v37, v114
	v_add_f32_e32 v43, v38, v40
	v_add_f32_e32 v40, v39, v41
	v_add_f32_e32 v42, v44, v112
	v_add_f32_e32 v41, v45, v36
	v_add_f32_e32 v43, v46, v43
	v_cvt_pk_bf16_f32 v36, v115, v116
	v_cvt_pk_bf16_f32 v37, v37, v38
	v_cvt_pk_bf16_f32 v38, v39, v44
	v_cvt_pk_bf16_f32 v39, v45, v46
	s_waitcnt lgkmcnt(1)
	v_mfma_f32_32x32x16_bf16 v[78:93], v[32:35], v[108:111], v[78:93]
	s_waitcnt lgkmcnt(0)
	s_barrier
	v_mad_u64_u32 v[32:33], s[18:19], s9, v237, v[132:133]
	global_load_dwordx4 v[112:115], v[32:33], off offset:2048
	global_load_dwordx4 v[116:119], v[136:137], off
	v_add_f32_e64 v32, v40, v42
	v_add_f32_e64 v33, v41, v43
	s_waitcnt vmcnt(4)
	ds_write_b128 v142, v[120:123]
	s_waitcnt vmcnt(3)
	ds_write_b128 v142, v[124:127] offset:8192
	v_mfma_f32_32x32x16_bf16 v[62:77], v[152:155], v[104:107], v[62:77]
	v_add_f32_e32 v32, v32, v33
	v_add_f32_e32 v150, v150, v32
	s_waitcnt lgkmcnt(2)
	v_mfma_f32_32x32x16_bf16 v[62:77], v[156:159], v[108:111], v[62:77]
	ds_read_b128 v[32:35], v144 offset:24576
	ds_read_b128 v[40:43], v144 offset:28672
	ds_read_b128 v[44:47], v141 offset:24576
	ds_read_b128 v[120:123], v141 offset:28672
	v_exp_f32_e32 v60, v78
	s_waitcnt lgkmcnt(3)
	v_mfma_f32_32x32x16_bf16 v[16:31], v[32:35], v[56:59], v[16:31]
	v_exp_f32_e32 v61, v79
	v_exp_f32_e32 v95, v80
	v_exp_f32_e32 v81, v81
	ds_read_b128 v[152:155], v140 offset:24576
	ds_read_b128 v[156:159], v140 offset:28672
	s_waitcnt lgkmcnt(4)
	v_mfma_f32_32x32x16_bf16 v[0:15], v[40:43], v[56:59], v[0:15]
	v_exp_f32_e32 v82, v82
	v_exp_f32_e32 v83, v83
	v_add_f32_e32 v78, v82, v60
	v_add_f32_e32 v79, v83, v61
	s_waitcnt lgkmcnt(2)
	v_mfma_f32_32x32x16_bf16 v[0:15], v[120:123], v[48:51], v[0:15]
	ds_read_b128 v[56:59], v139 offset:24576
	ds_read_b128 v[160:163], v139 offset:28672
	ds_read_b128 v[40:43], v164 offset:16384
	ds_read_b128 v[32:35], v164 offset:20480
	v_cvt_pk_bf16_f32 v82, v82, v83
	v_exp_f32_e32 v151, v62
	v_exp_f32_e32 v64, v64
	v_exp_f32_e32 v65, v65
	v_mfma_f32_32x32x16_bf16 v[16:31], v[44:47], v[48:51], v[16:31]
	v_exp_f32_e32 v44, v84
	v_exp_f32_e32 v45, v85
	v_exp_f32_e32 v84, v86
	v_exp_f32_e32 v85, v87
	v_add_f32_e32 v46, v44, v95
	v_add_f32_e32 v47, v45, v81
	v_add_f32_e32 v48, v84, v78
	s_waitcnt lgkmcnt(4)
	v_mfma_f32_32x32x16_bf16 v[0:15], v[156:159], v[52:55], v[0:15]
	v_add_f32_e32 v49, v85, v79
	v_exp_f32_e32 v78, v88
	v_exp_f32_e32 v79, v89
	v_exp_f32_e32 v87, v92
	v_cvt_pk_bf16_f32 v83, v44, v45
	v_exp_f32_e32 v44, v90
	v_mfma_f32_32x32x16_bf16 v[16:31], v[152:155], v[52:55], v[16:31]
	v_exp_f32_e32 v45, v91
	v_exp_f32_e32 v92, v93
	v_add_f32_e32 v46, v78, v46
	v_add_f32_e32 v47, v79, v47
	ds_read_b128 v[124:127], v165 offset:16384
	ds_read_b128 v[120:123], v165 offset:20480
	s_waitcnt lgkmcnt(4)
	v_mfma_f32_32x32x16_bf16 v[0:15], v[160:163], v[36:39], v[0:15]
	v_exp_f32_e32 v160, v63
	v_cvt_pk_bf16_f32 v80, v60, v61
	v_cvt_pk_bf16_f32 v81, v95, v81
	v_add_f32_e32 v48, v44, v48
	v_add_f32_e32 v49, v45, v49
	v_add_f32_e32 v46, v87, v46
	v_add_f32_e32 v47, v92, v47
	v_mfma_f32_32x32x16_bf16 v[16:31], v[56:59], v[36:39], v[16:31]
	v_add_f32_e32 v161, v151, v48
	v_add_f32_e32 v162, v160, v49
	v_cvt_pk_bf16_f32 v84, v84, v85
	v_cvt_pk_bf16_f32 v85, v78, v79
	v_cvt_pk_bf16_f32 v86, v44, v45
	v_add_f32_e32 v78, v64, v46
	v_add_f32_e32 v79, v65, v47
	s_waitcnt lgkmcnt(3)
	v_mfma_f32_32x32x16_bf16 v[48:63], v[40:43], v[96:99], 0
	ds_read_b128 v[88:91], v166 offset:16384
	ds_read_b128 v[152:155], v166 offset:20480
	v_exp_f32_e32 v66, v66
	v_exp_f32_e32 v67, v67
	v_exp_f32_e32 v68, v68
	v_exp_f32_e32 v69, v69
	v_cvt_pk_bf16_f32 v87, v87, v92
	s_waitcnt lgkmcnt(4)
	v_mfma_f32_32x32x16_bf16 v[32:47], v[32:35], v[96:99], 0
	ds_read_b128 v[156:159], v167 offset:16384
	ds_read_b128 v[92:95], v167 offset:20480
	v_add_f32_e32 v161, v66, v161
	v_add_f32_e32 v162, v67, v162
	v_add_f32_e32 v78, v68, v78
	v_add_f32_e32 v79, v69, v79
	s_waitcnt lgkmcnt(5)
	v_mfma_f32_32x32x16_bf16 v[48:63], v[124:127], v[100:103], v[48:63]
	v_exp_f32_e32 v70, v70
	v_exp_f32_e32 v71, v71
	s_add_i32 s9, s3, 2
	s_add_i32 s3, s3, -2
	v_lshl_add_u64 v[136:137], v[136:137], 0, s[22:23]
	s_waitcnt lgkmcnt(4)
	v_mfma_f32_32x32x16_bf16 v[32:47], v[120:123], v[100:103], v[32:47]
	v_add_f32_e32 v120, v70, v161
	v_add_f32_e32 v121, v71, v162
	s_cmp_lt_u32 s3, s2
	s_mov_b32 s3, s9
	s_waitcnt lgkmcnt(3)
	v_mfma_f32_32x32x16_bf16 v[48:63], v[88:91], v[104:107], v[48:63]
	v_cvt_pk_bf16_f32 v91, v68, v69
	v_exp_f32_e32 v68, v72
	v_exp_f32_e32 v69, v73
	v_exp_f32_e32 v72, v74
	v_exp_f32_e32 v73, v75
	v_exp_f32_e32 v74, v76
	v_exp_f32_e32 v75, v77
	s_waitcnt lgkmcnt(2)
	v_mfma_f32_32x32x16_bf16 v[32:47], v[152:155], v[104:107], v[32:47]
	v_cvt_pk_bf16_f32 v88, v151, v160
	v_cvt_pk_bf16_f32 v89, v64, v65
	v_cvt_pk_bf16_f32 v90, v66, v67
	v_add_f32_e32 v65, v68, v78
	v_add_f32_e32 v67, v69, v79
	s_waitcnt lgkmcnt(1)
	v_mfma_f32_32x32x16_bf16 v[48:63], v[156:159], v[108:111], v[48:63]
	v_add_f32_e32 v64, v72, v120
	v_add_f32_e32 v66, v73, v121
	v_add_f32_e32 v65, v74, v65
	v_add_f32_e32 v67, v75, v67
	s_waitcnt lgkmcnt(0)
	v_mfma_f32_32x32x16_bf16 v[32:47], v[92:95], v[108:111], v[32:47]
	v_cvt_pk_bf16_f32 v92, v70, v71
	v_cvt_pk_bf16_f32 v93, v68, v69
	v_cvt_pk_bf16_f32 v94, v72, v73
	v_cvt_pk_bf16_f32 v95, v74, v75
	v_add_f32_e64 v64, v64, v66
	v_add_f32_e64 v65, v65, v67
	s_waitcnt lgkmcnt(0)
	s_barrier
	v_add_f32_e32 v64, v64, v65
	v_add_f32_e32 v150, v150, v64
	s_cbranch_scc1 .LBB0_898
	v_ashrrev_i32_e32 v64, 1, v129
	v_and_or_b32 v132, v64, s88, v148
	v_lshlrev_b32_e32 v176, 4, v138
	s_waitcnt vmcnt(1)
	ds_write_b128 v142, v[112:115] offset:16384
	s_waitcnt vmcnt(0)
	ds_write_b128 v142, v[116:119] offset:24576
	ds_read_b128 v[124:127], v172 offset:32768
	ds_read_b128 v[120:123], v172 offset:40960
	ds_read_b128 v[116:119], v172 offset:49152
	ds_read_b128 v[112:115], v172 offset:57344
	v_ashrrev_i32_e32 v133, 31, v132
	ds_read_b128 v[128:131], v144 offset:8192
	ds_read_b128 v[134:137], v144 offset:12288
	ds_read_b128 v[146:149], v141 offset:8192
	ds_read_b128 v[152:155], v141 offset:12288
	v_exp_f32_e32 v138, v48
	v_exp_f32_e32 v142, v49
	s_waitcnt lgkmcnt(3)
	v_mfma_f32_32x32x16_bf16 v[16:31], v[128:131], v[80:83], v[16:31]
	v_exp_f32_e32 v151, v50
	v_add_f32_e32 v143, 0, v138
	v_add_f32_e32 v145, 0, v142
	v_exp_f32_e32 v156, v51
	ds_read_b128 v[48:51], v140 offset:8192
	ds_read_b128 v[128:131], v140 offset:12288
	v_exp_f32_e32 v52, v52
	s_waitcnt lgkmcnt(4)
	v_mfma_f32_32x32x16_bf16 v[0:15], v[134:137], v[80:83], v[0:15]
	v_exp_f32_e32 v53, v53
	v_exp_f32_e32 v54, v54
	v_exp_f32_e32 v55, v55
	v_add_f32_e32 v157, 0, v151
	v_add_f32_e32 v158, 0, v156
	v_add_f32_e32 v143, v52, v143
	s_waitcnt lgkmcnt(3)
	v_mfma_f32_32x32x16_bf16 v[16:31], v[146:149], v[84:87], v[16:31]
	v_add_f32_e32 v145, v53, v145
	v_add_f32_e32 v146, v54, v157
	ds_read_b128 v[80:83], v139 offset:8192
	ds_read_b128 v[134:137], v139 offset:12288
	v_exp_f32_e32 v56, v56
	v_exp_f32_e32 v57, v57
	v_exp_f32_e32 v58, v58
	s_waitcnt lgkmcnt(4)
	v_mfma_f32_32x32x16_bf16 v[0:15], v[152:155], v[84:87], v[0:15]
	v_add_f32_e32 v84, v55, v158
	v_exp_f32_e32 v59, v59
	v_exp_f32_e32 v60, v60
	v_exp_f32_e32 v32, v32
	v_exp_f32_e32 v33, v33
	v_exp_f32_e32 v34, v34
	s_waitcnt lgkmcnt(3)
	v_mfma_f32_32x32x16_bf16 v[16:31], v[48:51], v[88:91], v[16:31]
	v_cvt_pk_bf16_f32 v51, v54, v55
	v_exp_f32_e32 v54, v61
	v_exp_f32_e32 v55, v62
	v_exp_f32_e32 v61, v63
	v_exp_f32_e32 v35, v35
	v_add_f32_e32 v85, v56, v143
	v_add_f32_e32 v86, v57, v145
	v_add_f32_e32 v87, v58, v146
	v_add_f32_e32 v84, v59, v84
	v_cvt_pk_bf16_f32 v48, v138, v142
	v_cvt_pk_bf16_f32 v49, v151, v156
	v_cvt_pk_bf16_f32 v50, v52, v53
	v_add_f32_e32 v52, v60, v85
	v_add_f32_e32 v53, v54, v86
	v_add_f32_e32 v62, v55, v87
	v_add_f32_e32 v63, v61, v84
	v_exp_f32_e32 v36, v36
	v_exp_f32_e32 v37, v37
	v_exp_f32_e32 v38, v38
	v_exp_f32_e32 v39, v39
	s_waitcnt lgkmcnt(1)
	v_mfma_f32_32x32x16_bf16 v[16:31], v[80:83], v[92:95], v[16:31]
	v_add_f32_e32 v80, v32, v52
	v_add_f32_e32 v81, v33, v53
	v_cvt_pk_bf16_f32 v52, v56, v57
	v_cvt_pk_bf16_f32 v53, v58, v59
	v_cvt_pk_bf16_f32 v54, v60, v54
	v_cvt_pk_bf16_f32 v55, v55, v61
	v_add_f32_e32 v56, v34, v62
	v_add_f32_e32 v57, v35, v63
	v_exp_f32_e32 v40, v40
	v_add_f32_e32 v58, v36, v80
	v_add_f32_e32 v59, v37, v81
	v_add_f32_e32 v56, v38, v56
	v_exp_f32_e32 v41, v41
	v_add_f32_e32 v57, v39, v57
	v_mfma_f32_32x32x16_bf16 v[0:15], v[128:131], v[88:91], v[0:15]
	v_cvt_pk_bf16_f32 v32, v32, v33
	v_cvt_pk_bf16_f32 v33, v34, v35
	v_cvt_pk_bf16_f32 v34, v36, v37
	v_exp_f32_e32 v37, v42
	v_cvt_pk_bf16_f32 v35, v38, v39
	v_exp_f32_e32 v38, v43
	v_exp_f32_e32 v39, v44
	v_exp_f32_e32 v43, v45
	v_exp_f32_e32 v44, v46
	v_exp_f32_e32 v45, v47
	v_add_f32_e32 v58, v40, v58
	v_add_f32_e32 v59, v41, v59
	v_add_f32_e32 v36, v37, v56
	v_add_f32_e32 v42, v38, v57
	v_add_f32_e32 v56, v39, v58
	v_add_f32_e32 v58, v43, v59
	s_waitcnt lgkmcnt(0)
	v_mfma_f32_32x32x16_bf16 v[0:15], v[134:137], v[92:95], v[0:15]
	v_add_f32_e32 v57, v44, v36
	v_add_f32_e32 v59, v45, v42
	v_cvt_pk_bf16_f32 v36, v40, v41
	v_cvt_pk_bf16_f32 v37, v37, v38
	v_cvt_pk_bf16_f32 v38, v39, v43
	v_cvt_pk_bf16_f32 v39, v44, v45
	s_waitcnt lgkmcnt(0)
	s_barrier
	ds_read_b128 v[40:43], v144 offset:24576
	ds_read_b128 v[44:47], v144 offset:28672
	s_waitcnt lgkmcnt(1)
	v_mfma_f32_32x32x16_bf16 v[16:31], v[40:43], v[48:51], v[16:31]
	s_waitcnt lgkmcnt(0)
	v_mfma_f32_32x32x16_bf16 v[0:15], v[44:47], v[48:51], v[0:15]
	ds_read_b128 v[40:43], v141 offset:24576
	ds_read_b128 v[44:47], v141 offset:28672
	s_waitcnt lgkmcnt(1)
	v_mfma_f32_32x32x16_bf16 v[16:31], v[40:43], v[52:55], v[16:31]
	s_waitcnt lgkmcnt(0)
	v_mfma_f32_32x32x16_bf16 v[0:15], v[44:47], v[52:55], v[0:15]
	ds_read_b128 v[40:43], v140 offset:24576
	ds_read_b128 v[44:47], v140 offset:28672
	s_waitcnt lgkmcnt(1)
	v_mfma_f32_32x32x16_bf16 v[16:31], v[40:43], v[32:35], v[16:31]
	s_waitcnt lgkmcnt(0)
	v_mfma_f32_32x32x16_bf16 v[0:15], v[44:47], v[32:35], v[0:15]
	ds_read_b128 v[32:35], v139 offset:24576
	ds_read_b128 v[40:43], v139 offset:28672
	s_waitcnt lgkmcnt(1)
	v_mfma_f32_32x32x16_bf16 v[16:31], v[32:35], v[36:39], v[16:31]
	v_add_f32_e64 v32, v56, v58
	v_add_f32_e64 v33, v57, v59
	v_add_f32_e32 v32, v32, v33
	v_add_f32_e32 v32, v150, v32
	v_mov_b32_e32 v33, v32
	s_nop 1
	v_permlane32_swap_b32_e32 v32, v33
	v_add_f32_e32 v32, v32, v33
	v_div_scale_f32 v33, s[2:3], v32, v32, 1.0
	v_rcp_f32_e32 v34, v33
	s_waitcnt lgkmcnt(0)
	v_mfma_f32_32x32x16_bf16 v[0:15], v[40:43], v[36:39], v[0:15]
	s_waitcnt vmcnt(11)
	v_mov_b32_e32 v40, v127
	s_nop 1
	v_permlane32_swap_b32_e32 v125, v40
	v_fma_f32 v35, -v33, v34, 1.0
	v_fmac_f32_e32 v34, v35, v34
	v_div_scale_f32 v35, vcc, 1.0, v32, 1.0
	v_mul_f32_e32 v36, v35, v34
	v_fma_f32 v37, -v33, v36, v35
	v_fmac_f32_e32 v36, v37, v34
	v_fma_f32 v33, -v33, v36, v35
	v_div_fmas_f32 v33, v33, v34, v36
	v_mov_b32_e32 v35, v126
	v_div_fixup_f32 v34, v33, v32, 1.0
	s_nop 0
	v_permlane32_swap_b32_e32 v124, v35
	v_lshlrev_b32_e32 v38, 16, v124
	v_and_b32_e32 v39, 0xffff0000, v124
	v_mul_f32_e32 v16, v16, v34
	v_mul_f32_e32 v17, v17, v34
	v_mul_f32_e32 v18, v18, v34
	v_mul_f32_e32 v19, v19, v34
	v_mul_f32_e32 v16, v16, v38
	v_mul_f32_e32 v17, v17, v39
	v_lshlrev_b32_e32 v38, 16, v125
	v_and_b32_e32 v39, 0xffff0000, v125
	v_mul_f32_e32 v18, v18, v38
	v_mul_f32_e32 v19, v19, v39
	v_cvt_pk_bf16_f32 v16, v16, v17
	v_cvt_pk_bf16_f32 v17, v18, v19
	v_lshlrev_b32_e32 v18, 16, v35
	v_and_b32_e32 v19, 0xffff0000, v35
	v_mul_f32_e32 v20, v20, v34
	v_mul_f32_e32 v21, v21, v34
	v_mul_f32_e32 v22, v22, v34
	v_mul_f32_e32 v23, v23, v34
	v_mul_f32_e32 v18, v20, v18
	v_mul_f32_e32 v19, v21, v19
	v_lshlrev_b32_e32 v20, 16, v40
	v_and_b32_e32 v21, 0xffff0000, v40
	v_lshlrev_b64 v[32:33], 11, v[132:133]
	v_mul_f32_e32 v20, v22, v20
	v_mul_f32_e32 v21, v23, v21
	v_lshl_add_u64 v[32:33], s[6:7], 0, v[32:33]
	v_cvt_pk_bf16_f32 v18, v18, v19
	v_cvt_pk_bf16_f32 v19, v20, v21
	s_waitcnt vmcnt(10)
	v_mov_b32_e32 v22, v122
	v_lshl_add_u64 v[36:37], v[32:33], 0, v[176:177]
	v_permlane32_swap_b32_e32 v16, v18
	v_permlane32_swap_b32_e32 v17, v19
	v_permlane32_swap_b32_e32 v120, v22
	v_mov_b32_e32 v23, v123
	global_store_dwordx4 v[36:37], v[16:19], off offset:512
	s_nop 0
	v_permlane32_swap_b32_e32 v121, v23
	v_lshlrev_b32_e32 v16, 16, v120
	v_and_b32_e32 v17, 0xffff0000, v120
	v_mul_f32_e32 v18, v24, v34
	v_mul_f32_e32 v19, v25, v34
	v_mul_f32_e32 v20, v26, v34
	v_mul_f32_e32 v21, v27, v34
	v_mul_f32_e32 v16, v18, v16
	v_mul_f32_e32 v17, v19, v17
	v_lshlrev_b32_e32 v18, 16, v121
	v_and_b32_e32 v19, 0xffff0000, v121
	v_mul_f32_e32 v18, v20, v18
	v_mul_f32_e32 v19, v21, v19
	v_cvt_pk_bf16_f32 v16, v16, v17
	v_cvt_pk_bf16_f32 v17, v18, v19
	v_lshlrev_b32_e32 v18, 16, v22
	v_and_b32_e32 v19, 0xffff0000, v22
	v_mul_f32_e32 v20, v28, v34
	v_mul_f32_e32 v21, v29, v34
	v_mul_f32_e32 v0, v0, v34
	v_mul_f32_e32 v1, v1, v34
	v_mul_f32_e32 v18, v20, v18
	v_mul_f32_e32 v19, v21, v19
	v_lshlrev_b32_e32 v20, 16, v23
	v_and_b32_e32 v21, 0xffff0000, v23
	v_mul_f32_e32 v22, v30, v34
	v_mul_f32_e32 v23, v31, v34
	v_cvt_pk_bf16_f32 v18, v18, v19
	v_mul_f32_e32 v20, v22, v20
	v_mul_f32_e32 v21, v23, v21
	s_nop 0
	v_permlane32_swap_b32_e32 v16, v18
	v_cvt_pk_bf16_f32 v19, v20, v21
	s_nop 1
	v_permlane32_swap_b32_e32 v17, v19
	global_store_dwordx4 v[36:37], v[16:19], off offset:544
	v_mul_f32_e32 v2, v2, v34
	v_mul_f32_e32 v3, v3, v34
	v_mul_f32_e32 v4, v4, v34
	v_mul_f32_e32 v5, v5, v34
	s_waitcnt vmcnt(11)
	v_mov_b32_e32 v18, v118
	s_nop 1
	v_permlane32_swap_b32_e32 v116, v18
	v_mov_b32_e32 v19, v119
	s_nop 1
	v_permlane32_swap_b32_e32 v117, v19
	v_lshlrev_b32_e32 v16, 16, v116
	v_and_b32_e32 v17, 0xffff0000, v116
	v_mul_f32_e32 v0, v0, v16
	v_mul_f32_e32 v1, v1, v17
	v_lshlrev_b32_e32 v16, 16, v117
	v_and_b32_e32 v17, 0xffff0000, v117
	v_mul_f32_e32 v2, v2, v16
	v_mul_f32_e32 v3, v3, v17
	v_cvt_pk_bf16_f32 v0, v0, v1
	v_cvt_pk_bf16_f32 v1, v2, v3
	v_lshlrev_b32_e32 v2, 16, v18
	v_and_b32_e32 v3, 0xffff0000, v18
	v_mul_f32_e32 v2, v4, v2
	v_mul_f32_e32 v3, v5, v3
	v_lshlrev_b32_e32 v4, 16, v19
	v_and_b32_e32 v5, 0xffff0000, v19
	v_mul_f32_e32 v6, v6, v34
	v_mul_f32_e32 v7, v7, v34
	v_cvt_pk_bf16_f32 v2, v2, v3
	v_mul_f32_e32 v4, v6, v4
	v_mul_f32_e32 v5, v7, v5
	s_waitcnt vmcnt(10)
	v_mov_b32_e32 v6, v114
	v_cvt_pk_bf16_f32 v3, v4, v5
	v_permlane32_swap_b32_e32 v0, v2
	s_nop 0
	v_permlane32_swap_b32_e32 v1, v3
	v_permlane32_swap_b32_e32 v112, v6
	v_mov_b32_e32 v7, v115
	global_store_dwordx4 v[36:37], v[0:3], off offset:576
	s_nop 0
	v_permlane32_swap_b32_e32 v113, v7
	v_lshlrev_b32_e32 v0, 16, v112
	v_and_b32_e32 v1, 0xffff0000, v112
	v_mul_f32_e32 v2, v8, v34
	v_mul_f32_e32 v3, v9, v34
	v_mul_f32_e32 v4, v10, v34
	v_mul_f32_e32 v5, v11, v34
	v_mul_f32_e32 v0, v2, v0
	v_mul_f32_e32 v1, v3, v1
	v_lshlrev_b32_e32 v2, 16, v113
	v_and_b32_e32 v3, 0xffff0000, v113
	v_mul_f32_e32 v2, v4, v2
	v_mul_f32_e32 v3, v5, v3
	v_cvt_pk_bf16_f32 v0, v0, v1
	v_cvt_pk_bf16_f32 v1, v2, v3
	v_lshlrev_b32_e32 v2, 16, v6
	v_and_b32_e32 v3, 0xffff0000, v6
	v_mul_f32_e32 v4, v12, v34
	v_mul_f32_e32 v5, v13, v34
	s_mov_b64 s[2:3], 0x200
	v_mul_f32_e32 v2, v4, v2
	v_mul_f32_e32 v3, v5, v3
	v_lshlrev_b32_e32 v4, 16, v7
	v_and_b32_e32 v5, 0xffff0000, v7
	v_mul_f32_e32 v6, v14, v34
	v_mul_f32_e32 v7, v15, v34
	v_cvt_pk_bf16_f32 v2, v2, v3
	v_mul_f32_e32 v4, v6, v4
	v_mul_f32_e32 v5, v7, v5
	v_lshl_add_u64 v[32:33], v[36:37], 0, s[2:3]
	v_cvt_pk_bf16_f32 v3, v4, v5
	v_permlane32_swap_b32_e32 v0, v2
	s_nop 0
	v_permlane32_swap_b32_e32 v1, v3
	s_branch .LBB0_876
